# small stack: rstd prefill loads batched, unread halo rows of the last 64-row block not written, unused barrier generation atomics dropped
# speedup vs baseline: 1.0176x; 1.0011x over previous
.LBB0_398:
	s_or_b64 exec, exec, s[12:13]
	v_cvt_f32_u32_e32 v4, v0
	s_waitcnt vmcnt(0)
	v_readfirstlane_b32 s10, v3
	v_sub_u32_e32 v3, 0, v0
	s_mov_b64 s[12:13], 0
	v_rcp_iflag_f32_e32 v4, v4
	v_add_u32_e32 v1, s10, v1
	v_add_u32_e32 v5, 1, v1
	v_mul_f32_e32 v4, 0x4f7ffffe, v4
	v_cvt_u32_f32_e32 v4, v4
	v_mul_lo_u32 v3, v3, v4
	v_mul_hi_u32 v3, v4, v3
	v_add_u32_e32 v3, v4, v3
	v_mul_hi_u32 v3, v1, v3
	v_mul_lo_u32 v4, v3, v0
	v_sub_u32_e32 v1, v1, v4
	v_add_u32_e32 v6, 1, v3
	v_sub_u32_e32 v4, v1, v0
	v_cmp_ge_u32_e32 vcc, v1, v0
	s_nop 1
	v_cndmask_b32_e32 v3, v3, v6, vcc
	v_cndmask_b32_e32 v1, v1, v4, vcc
	v_add_u32_e32 v4, 1, v3
	v_cmp_ge_u32_e32 vcc, v1, v0
	s_nop 1
	v_cndmask_b32_e32 v3, v3, v4, vcc
	v_mul_lo_u32 v1, v0, v3
	v_add_u32_e32 v0, v1, v0
	v_cmp_ne_u32_e32 vcc, v5, v0
	v_mov_b32_e32 v7, v0
	v_mov_b64_e32 v[0:1], s[40:41]
	s_and_saveexec_b64 s[10:11], vcc
	s_cbranch_execz .LBB0_410
	global_load_dword v0, v2, s[40:41] offset:-256 sc1
	s_mov_b64 s[14:15], 0
	s_waitcnt vmcnt(0)
	v_cmp_lt_u32_e32 vcc, v0, v7
	s_and_saveexec_b64 s[12:13], vcc
	s_cbranch_execz .LBB0_409
	s_mov_b32 s25, 1
	s_branch .LBB0_402

.LBB0_412:
	s_or_b64 exec, exec, s[10:11]
	s_mov_b64 s[10:11], exec
	v_mbcnt_lo_u32_b32 v0, s10, 0
	v_mbcnt_hi_u32_b32 v0, s11, v0
	v_cmp_eq_u32_e32 vcc, 0, v0
	s_waitcnt vmcnt(0)
	s_and_saveexec_b64 s[12:13], vcc
	s_cbranch_execz .LBB0_414
	s_add_i32 s94, s24, 0x900
	s_lshl_b64 s[14:15], s[94:95], 2
	s_add_u32 s14, s92, s14
	s_addc_u32 s15, s93, s15
	s_bcnt1_i32_b64 s10, s[10:11]
	v_mov_b32_e32 v0, s10
	v_readlane_b32 s94, v253, 3
	v_readlane_b32 s87, v254, 62

.LBB0_453:
	s_or_b64 exec, exec, s[12:13]
	s_waitcnt vmcnt(0)
	v_readfirstlane_b32 s10, v3
	v_cvt_f32_u32_e32 v3, v0
	v_sub_u32_e32 v4, 0, v0
	v_add_u32_e32 v1, s10, v1
	s_mov_b64 s[12:13], 0
	v_rcp_iflag_f32_e32 v3, v3
	s_nop 0
	v_mul_f32_e32 v3, 0x4f7ffffe, v3
	v_cvt_u32_f32_e32 v3, v3
	v_mul_lo_u32 v4, v4, v3
	v_mul_hi_u32 v4, v3, v4
	v_add_u32_e32 v3, v3, v4
	v_mul_hi_u32 v3, v1, v3
	v_mul_lo_u32 v4, v3, v0
	v_sub_u32_e32 v4, v1, v4
	v_cmp_ge_u32_e32 vcc, v4, v0
	v_add_u32_e32 v5, 1, v3
	v_add_u32_e32 v1, 1, v1
	v_cndmask_b32_e32 v3, v3, v5, vcc
	v_sub_u32_e32 v5, v4, v0
	v_cndmask_b32_e32 v4, v4, v5, vcc
	v_cmp_ge_u32_e32 vcc, v4, v0
	v_add_u32_e32 v4, 1, v3
	s_nop 0
	v_cndmask_b32_e32 v3, v3, v4, vcc
	v_mul_lo_u32 v4, v0, v3
	v_add_u32_e32 v0, v4, v0
	v_cmp_ne_u32_e32 vcc, v1, v0
	v_mov_b32_e32 v7, v0
	v_mov_b64_e32 v[0:1], s[40:41]
	s_and_saveexec_b64 s[10:11], vcc
	s_cbranch_execz .LBB0_465
	global_load_dword v0, v2, s[40:41] offset:-256 sc1
	s_mov_b64 s[14:15], 0
	s_waitcnt vmcnt(0)
	v_cmp_lt_u32_e32 vcc, v0, v7
	s_and_saveexec_b64 s[12:13], vcc
	s_cbranch_execz .LBB0_464
	s_mov_b32 s25, 1
	s_branch .LBB0_457

.LBB0_648:
	s_or_b64 exec, exec, s[12:13]
	s_waitcnt vmcnt(0)
	v_readfirstlane_b32 s7, v3
	v_cvt_f32_u32_e32 v3, v0
	v_sub_u32_e32 v4, 0, v0
	v_add_u32_e32 v1, s7, v1
	s_mov_b64 s[12:13], 0
	v_rcp_iflag_f32_e32 v3, v3
	s_nop 0
	v_mul_f32_e32 v3, 0x4f7ffffe, v3
	v_cvt_u32_f32_e32 v3, v3
	v_mul_lo_u32 v4, v4, v3
	v_mul_hi_u32 v4, v3, v4
	v_add_u32_e32 v3, v3, v4
	v_mul_hi_u32 v3, v1, v3
	v_mul_lo_u32 v4, v3, v0
	v_sub_u32_e32 v4, v1, v4
	v_cmp_ge_u32_e32 vcc, v4, v0
	v_add_u32_e32 v5, 1, v3
	v_add_u32_e32 v1, 1, v1
	v_cndmask_b32_e32 v3, v3, v5, vcc
	v_sub_u32_e32 v5, v4, v0
	v_cndmask_b32_e32 v4, v4, v5, vcc
	v_cmp_ge_u32_e32 vcc, v4, v0
	v_add_u32_e32 v4, 1, v3
	s_nop 0
	v_cndmask_b32_e32 v3, v3, v4, vcc
	v_mul_lo_u32 v4, v0, v3
	v_add_u32_e32 v0, v4, v0
	v_cmp_ne_u32_e32 vcc, v1, v0
	v_mov_b32_e32 v7, v0
	v_mov_b64_e32 v[0:1], s[40:41]
	s_and_saveexec_b64 s[10:11], vcc
	s_cbranch_execz .LBB0_660
	global_load_dword v0, v2, s[40:41] offset:-256 sc1
	s_mov_b64 s[14:15], 0
	s_waitcnt vmcnt(0)
	v_cmp_lt_u32_e32 vcc, v0, v7
	s_and_saveexec_b64 s[12:13], vcc
	s_cbranch_execz .LBB0_659
	s_mov_b32 s7, 1
	s_branch .LBB0_652

.LBB0_662:
	s_or_b64 exec, exec, s[10:11]
	s_mov_b64 s[10:11], exec
	v_mbcnt_lo_u32_b32 v0, s10, 0
	v_mbcnt_hi_u32_b32 v0, s11, v0
	v_cmp_eq_u32_e32 vcc, 0, v0
	s_waitcnt vmcnt(0)
	s_and_saveexec_b64 s[12:13], vcc
	s_cbranch_execz .LBB0_664
	s_add_i32 s94, s6, 0x900
	s_lshl_b64 s[6:7], s[94:95], 2
	s_add_u32 s6, s92, s6
	s_addc_u32 s7, s93, s7
	s_bcnt1_i32_b64 s10, s[10:11]
	v_mov_b32_e32 v0, s10
	v_readlane_b32 s94, v253, 3
	v_readlane_b32 s87, v254, 62

.LBB0_684:
	v_lshlrev_b32_e32 v132, 4, v206
	v_add3_u32 v133, s87, v157, v132
	v_lshlrev_b32_e32 v133, 3, v133
	v_add_u32_e32 v133, 0x22800, v133
	s_lshl_b32 s10, s16, 10
	s_lshl_b32 s11, s79, 2
	s_add_i32 s10, s10, s11
	s_add_i32 s10, s10, 0x23800
	v_lshl_add_u32 v154, v157, 4, s10
	ds_read_b128 v[150:153], v154
	ds_read_b128 v[158:161], v154 offset:512
	s_waitcnt vmcnt(16)
	ds_write_b64 v133, v[182:183]
	v_add_u32_e32 v155, s92, v132
	v_lshlrev_b32_e32 v204, 5, v206
	s_lshl_b32 s11, s84, 2
	s_add_i32 s11, s11, 0x22800
	v_add_u32_e32 v204, s11, v204
	v_add_u32_e32 v205, 0xfffff800, v155
	v_lshlrev_b32_e32 v221, 9, v157
	v_add_u32_e32 v221, v221, v132
	v_lshlrev_b32_e32 v3, 5, v206
	v_cmp_eq_u32_e64 s[56:57], 15, v157
	s_mul_i32 s14, s48, 0x160000
	s_lshl_b32 s15, s19, 9
	s_add_i32 s14, s14, s15
	s_lshr_b32 s15, s84, 6
	s_lshl_b32 s15, s15, 15
	s_add_i32 s14, s14, s15
	s_lshl_b32 s15, s79, 7
	s_add_i32 s14, s14, s15
	s_and_b32 s15, s84, 32
	s_lshl_b32 s15, s15, 1
	s_add_i32 s14, s14, s15
	s_add_u32 s14, s20, s14
	s_addc_u32 s15, s21, 0
	s_add_u32 s50, s14, 0x4000
	s_addc_u32 s51, s15, 0
	s_mul_i32 s41, s48, 0xb000
	s_lshl_b32 s49, s19, 3
	s_add_i32 s41, s41, s49
	s_lshl_b32 s49, s84, 2
	s_add_i32 s41, s41, s49
	s_mov_b32 s10, 0xbfb8aa3b
	s_mov_b32 s11, 0xbfb8aa3b
	s_mov_b32 s12, 1.0
	s_mov_b32 s13, 1.0
	s_waitcnt lgkmcnt(0)
	v_pk_mul_f32 v[120:121], v[120:121], v[152:153] op_sel_hi:[1,0]
	v_pk_mul_f32 v[122:123], v[122:123], v[152:153] op_sel_hi:[1,0]
	v_pk_mul_f32 v[116:117], v[116:117], v[152:153] op_sel:[0,1]
	v_pk_mul_f32 v[118:119], v[118:119], v[152:153] op_sel:[0,1]
	v_pk_mul_f32 v[104:105], v[104:105], v[152:153] op_sel_hi:[1,0]
	v_pk_mul_f32 v[106:107], v[106:107], v[152:153] op_sel_hi:[1,0]
	v_pk_mul_f32 v[100:101], v[100:101], v[152:153] op_sel:[0,1]
	v_pk_mul_f32 v[102:103], v[102:103], v[152:153] op_sel:[0,1]
	v_pk_mul_f32 v[88:89], v[88:89], v[152:153] op_sel_hi:[1,0]
	v_pk_mul_f32 v[90:91], v[90:91], v[152:153] op_sel_hi:[1,0]
	v_pk_mul_f32 v[84:85], v[84:85], v[152:153] op_sel:[0,1]
	v_pk_mul_f32 v[86:87], v[86:87], v[152:153] op_sel:[0,1]
	v_pk_mul_f32 v[72:73], v[72:73], v[152:153] op_sel_hi:[1,0]
	v_pk_mul_f32 v[74:75], v[74:75], v[152:153] op_sel_hi:[1,0]
	v_pk_mul_f32 v[68:69], v[68:69], v[152:153] op_sel:[0,1]
	v_pk_mul_f32 v[70:71], v[70:71], v[152:153] op_sel:[0,1]
	v_pk_mul_f32 v[56:57], v[56:57], v[160:161] op_sel_hi:[1,0]
	v_pk_mul_f32 v[58:59], v[58:59], v[160:161] op_sel_hi:[1,0]
	v_pk_mul_f32 v[52:53], v[52:53], v[160:161] op_sel:[0,1]
	v_pk_mul_f32 v[54:55], v[54:55], v[160:161] op_sel:[0,1]
	v_pk_mul_f32 v[40:41], v[40:41], v[160:161] op_sel_hi:[1,0]
	v_pk_mul_f32 v[42:43], v[42:43], v[160:161] op_sel_hi:[1,0]
	v_pk_mul_f32 v[36:37], v[36:37], v[160:161] op_sel:[0,1]
	v_pk_mul_f32 v[38:39], v[38:39], v[160:161] op_sel:[0,1]
	v_pk_mul_f32 v[24:25], v[24:25], v[160:161] op_sel_hi:[1,0]
	v_pk_mul_f32 v[26:27], v[26:27], v[160:161] op_sel_hi:[1,0]
	v_pk_mul_f32 v[20:21], v[20:21], v[160:161] op_sel:[0,1]
	v_pk_mul_f32 v[22:23], v[22:23], v[160:161] op_sel:[0,1]
	v_pk_mul_f32 v[8:9], v[8:9], v[160:161] op_sel_hi:[1,0]
	v_pk_mul_f32 v[10:11], v[10:11], v[160:161] op_sel_hi:[1,0]
	v_pk_mul_f32 v[4:5], v[4:5], v[160:161] op_sel:[0,1]
	v_pk_mul_f32 v[6:7], v[6:7], v[160:161] op_sel:[0,1]
	s_and_saveexec_b64 s[52:53], s[56:57]
	ds_write_b128 v155, v[120:123] offset:0
	ds_write_b128 v155, v[116:119] offset:256
	ds_write_b128 v155, v[88:91] offset:64
	ds_write_b128 v155, v[84:87] offset:320
	ds_write_b128 v155, v[104:107] offset:128
	ds_write_b128 v155, v[100:103] offset:384
	ds_write_b128 v155, v[72:75] offset:192
	ds_write_b128 v155, v[68:71] offset:448
	s_cmp_lg_u32 s79, 0
	s_cbranch_scc1 .Lup_nohalo
	ds_write_b128 v155, v[56:59] offset:4096
	ds_write_b128 v155, v[52:55] offset:4352
	ds_write_b128 v155, v[24:27] offset:4160
	ds_write_b128 v155, v[20:23] offset:4416
	ds_write_b128 v155, v[40:43] offset:4224
	ds_write_b128 v155, v[36:39] offset:4480
	ds_write_b128 v155, v[8:11] offset:4288
	ds_write_b128 v155, v[4:7] offset:4544
.Lup_nohalo:
	s_mov_b64 exec, s[52:53]
	v_pk_mul_f32 v[128:129], v[128:129], v[150:151] op_sel_hi:[1,0]
	v_pk_mul_f32 v[130:131], v[130:131], v[150:151] op_sel_hi:[1,0]
	v_pk_mul_f32 v[124:125], v[124:125], v[150:151] op_sel:[0,1]
	v_pk_mul_f32 v[126:127], v[126:127], v[150:151] op_sel:[0,1]
	v_pk_mul_f32 v[112:113], v[112:113], v[150:151] op_sel_hi:[1,0]
	v_pk_mul_f32 v[114:115], v[114:115], v[150:151] op_sel_hi:[1,0]
	v_pk_mul_f32 v[108:109], v[108:109], v[150:151] op_sel:[0,1]
	v_pk_mul_f32 v[110:111], v[110:111], v[150:151] op_sel:[0,1]
	v_pk_mul_f32 v[96:97], v[96:97], v[150:151] op_sel_hi:[1,0]
	v_pk_mul_f32 v[98:99], v[98:99], v[150:151] op_sel_hi:[1,0]
	v_pk_mul_f32 v[92:93], v[92:93], v[150:151] op_sel:[0,1]
	v_pk_mul_f32 v[94:95], v[94:95], v[150:151] op_sel:[0,1]
	v_pk_mul_f32 v[80:81], v[80:81], v[150:151] op_sel_hi:[1,0]
	v_pk_mul_f32 v[82:83], v[82:83], v[150:151] op_sel_hi:[1,0]
	v_pk_mul_f32 v[76:77], v[76:77], v[150:151] op_sel:[0,1]
	v_pk_mul_f32 v[78:79], v[78:79], v[150:151] op_sel:[0,1]
	v_pk_mul_f32 v[64:65], v[64:65], v[158:159] op_sel_hi:[1,0]
	v_pk_mul_f32 v[66:67], v[66:67], v[158:159] op_sel_hi:[1,0]
	v_pk_mul_f32 v[60:61], v[60:61], v[158:159] op_sel:[0,1]
	v_pk_mul_f32 v[62:63], v[62:63], v[158:159] op_sel:[0,1]
	v_pk_mul_f32 v[48:49], v[48:49], v[158:159] op_sel_hi:[1,0]
	v_pk_mul_f32 v[50:51], v[50:51], v[158:159] op_sel_hi:[1,0]
	v_pk_mul_f32 v[44:45], v[44:45], v[158:159] op_sel:[0,1]
	v_pk_mul_f32 v[46:47], v[46:47], v[158:159] op_sel:[0,1]
	v_pk_mul_f32 v[32:33], v[32:33], v[158:159] op_sel_hi:[1,0]
	v_pk_mul_f32 v[34:35], v[34:35], v[158:159] op_sel_hi:[1,0]
	v_pk_mul_f32 v[28:29], v[28:29], v[158:159] op_sel:[0,1]
	v_pk_mul_f32 v[30:31], v[30:31], v[158:159] op_sel:[0,1]
	v_pk_mul_f32 v[16:17], v[16:17], v[158:159] op_sel_hi:[1,0]
	v_pk_mul_f32 v[18:19], v[18:19], v[158:159] op_sel_hi:[1,0]
	v_pk_mul_f32 v[12:13], v[12:13], v[158:159] op_sel:[0,1]
	v_pk_mul_f32 v[14:15], v[14:15], v[158:159] op_sel:[0,1]
	s_waitcnt lgkmcnt(0)
	s_barrier
	ds_read_b128 v[134:137], v204 offset:0
	ds_read_b128 v[138:141], v204 offset:1024
	ds_read_b128 v[142:145], v204 offset:2048
	ds_read_b128 v[146:149], v204 offset:3072
	ds_read_b128 v[222:225], v205 offset:0
	ds_read_b128 v[226:229], v205 offset:256
	ds_read_b128 v[230:233], v205 offset:4096
	ds_read_b128 v[234:237], v205 offset:4352
	ds_read_b128 v[184:187], v204 offset:512
	ds_read_b128 v[188:191], v204 offset:1536
	ds_read_b128 v[192:195], v204 offset:2560
	ds_read_b128 v[196:199], v204 offset:3584
	s_waitcnt lgkmcnt(6)
	s_and_b64 vcc, exec, s[28:29]
	s_cbranch_vccz .Lup_z000
	v_mov_b32_dpp v226, v116 row_shr:1 row_mask:0xf bank_mask:0xf
	v_mov_b32_dpp v227, v117 row_shr:1 row_mask:0xf bank_mask:0xf
	v_mov_b32_dpp v228, v118 row_shr:1 row_mask:0xf bank_mask:0xf
	v_mov_b32_dpp v229, v119 row_shr:1 row_mask:0xf bank_mask:0xf
	v_mov_b32_dpp v222, v120 row_shr:1 row_mask:0xf bank_mask:0xf
	v_mov_b32_dpp v223, v121 row_shr:1 row_mask:0xf bank_mask:0xf
	v_mov_b32_dpp v224, v122 row_shr:1 row_mask:0xf bank_mask:0xf
	v_mov_b32_dpp v225, v123 row_shr:1 row_mask:0xf bank_mask:0xf
	s_branch .Lup_d000

.LBB0_776:
	s_or_b64 exec, exec, s[14:15]
	s_waitcnt vmcnt(0)
	v_readfirstlane_b32 s7, v3
	v_cvt_f32_u32_e32 v3, v0
	v_sub_u32_e32 v4, 0, v0
	v_add_u32_e32 v1, s7, v1
	s_mov_b64 s[14:15], 0
	v_rcp_iflag_f32_e32 v3, v3
	s_nop 0
	v_mul_f32_e32 v3, 0x4f7ffffe, v3
	v_cvt_u32_f32_e32 v3, v3
	v_mul_lo_u32 v4, v4, v3
	v_mul_hi_u32 v4, v3, v4
	v_add_u32_e32 v3, v3, v4
	v_mul_hi_u32 v3, v1, v3
	v_mul_lo_u32 v4, v3, v0
	v_sub_u32_e32 v4, v1, v4
	v_cmp_ge_u32_e32 vcc, v4, v0
	v_add_u32_e32 v5, 1, v3
	v_add_u32_e32 v1, 1, v1
	v_cndmask_b32_e32 v3, v3, v5, vcc
	v_sub_u32_e32 v5, v4, v0
	v_cndmask_b32_e32 v4, v4, v5, vcc
	v_cmp_ge_u32_e32 vcc, v4, v0
	v_add_u32_e32 v4, 1, v3
	s_nop 0
	v_cndmask_b32_e32 v3, v3, v4, vcc
	v_mul_lo_u32 v4, v0, v3
	v_add_u32_e32 v0, v4, v0
	v_cmp_ne_u32_e32 vcc, v1, v0
	v_mov_b32_e32 v7, v0
	v_mov_b64_e32 v[0:1], s[40:41]
	s_and_saveexec_b64 s[12:13], vcc
	s_cbranch_execz .LBB0_788
	global_load_dword v0, v2, s[40:41] offset:-256 sc1
	s_mov_b64 s[16:17], 0
	s_waitcnt vmcnt(0)
	v_cmp_lt_u32_e32 vcc, v0, v7
	s_and_saveexec_b64 s[14:15], vcc
	s_cbranch_execz .LBB0_787
	s_mov_b32 s7, 1
	s_branch .LBB0_780

.LBB0_790:
	s_or_b64 exec, exec, s[12:13]
	s_mov_b64 s[12:13], exec
	v_mbcnt_lo_u32_b32 v0, s12, 0
	v_mbcnt_hi_u32_b32 v0, s13, v0
	v_cmp_eq_u32_e32 vcc, 0, v0
	s_waitcnt vmcnt(0)
	s_and_saveexec_b64 s[14:15], vcc
	s_cbranch_execz .LBB0_792
	s_add_i32 s94, s6, 0x900
	s_lshl_b64 s[6:7], s[94:95], 2
	s_add_u32 s6, s92, s6
	s_addc_u32 s7, s93, s7
	s_bcnt1_i32_b64 s12, s[12:13]
	v_mov_b32_e32 v0, s12
	v_readlane_b32 s94, v253, 3
	v_readlane_b32 s87, v254, 62

.LBB0_893:
	s_or_b64 exec, exec, s[10:11]
	s_waitcnt vmcnt(0)
	v_readfirstlane_b32 s8, v3
	v_cvt_f32_u32_e32 v3, v0
	v_sub_u32_e32 v4, 0, v0
	v_add_u32_e32 v1, s8, v1
	s_mov_b64 s[10:11], 0
	v_rcp_iflag_f32_e32 v3, v3
	s_nop 0
	v_mul_f32_e32 v3, 0x4f7ffffe, v3
	v_cvt_u32_f32_e32 v3, v3
	v_mul_lo_u32 v4, v4, v3
	v_mul_hi_u32 v4, v3, v4
	v_add_u32_e32 v3, v3, v4
	v_mul_hi_u32 v3, v1, v3
	v_mul_lo_u32 v4, v3, v0
	v_sub_u32_e32 v4, v1, v4
	v_cmp_ge_u32_e32 vcc, v4, v0
	v_add_u32_e32 v5, 1, v3
	v_add_u32_e32 v1, 1, v1
	v_cndmask_b32_e32 v3, v3, v5, vcc
	v_sub_u32_e32 v5, v4, v0
	v_cndmask_b32_e32 v4, v4, v5, vcc
	v_cmp_ge_u32_e32 vcc, v4, v0
	v_add_u32_e32 v4, 1, v3
	s_nop 0
	v_cndmask_b32_e32 v3, v3, v4, vcc
	v_mul_lo_u32 v4, v0, v3
	v_add_u32_e32 v0, v4, v0
	v_cmp_ne_u32_e32 vcc, v1, v0
	v_mov_b32_e32 v7, v0
	v_mov_b64_e32 v[0:1], s[40:41]
	s_and_saveexec_b64 s[8:9], vcc
	s_cbranch_execz .LBB0_905
	global_load_dword v0, v2, s[40:41] offset:-256 sc1
	s_mov_b64 s[12:13], 0
	s_waitcnt vmcnt(0)
	v_cmp_lt_u32_e32 vcc, v0, v7
	s_and_saveexec_b64 s[10:11], vcc
	s_cbranch_execz .LBB0_904
	s_mov_b32 s22, 1
	s_branch .LBB0_897

.LBB0_907:
	s_or_b64 exec, exec, s[8:9]
	s_mov_b64 s[8:9], exec
	v_mbcnt_lo_u32_b32 v0, s8, 0
	v_mbcnt_hi_u32_b32 v0, s9, v0
	v_cmp_eq_u32_e32 vcc, 0, v0
	s_waitcnt vmcnt(0)
	s_and_saveexec_b64 s[10:11], vcc
	s_cbranch_execz .LBB0_130
	s_add_i32 s94, s24, 0x900
	s_lshl_b64 s[12:13], s[94:95], 2
	s_add_u32 s12, s92, s12
	s_addc_u32 s13, s93, s13
	s_bcnt1_i32_b64 s8, s[8:9]
	v_mov_b32_e32 v0, s8
	v_readlane_b32 s94, v253, 3
	v_readlane_b32 s87, v254, 62
	s_branch .LBB0_130
